# eleven of the twelve residual-tile pieces per lane on chip between residual-GEMM epilogues (4 in spare LDS, 7 in VGPRs unused elsewhere)
# speedup vs baseline: 1.0307x; 1.0114x over previous
.LBB0_890:
	v_readlane_b32 s98, v254, 41
	v_readlane_b32 s99, v254, 51
	v_readlane_b32 s100, v254, 11
	s_or_b32 s98, s98, s99
	v_readlane_b32 s99, v254, 5
	s_cmp_lg_u32 s100, 0
	s_cselect_b32 s100, 0x4000, 0
	s_lshl_b32 s99, s99, 7
	s_add_u32 s99, s99, s100
	s_add_u32 s99, s99, 131088
	s_cmp_eq_u32 s98, 0
	s_cbranch_scc1 .Lxr_t0
	v_mov_b32_e32 v114, v244
	v_mov_b32_e32 v115, v245
	v_mov_b32_e32 v116, v250
	v_mov_b32_e32 v117, v251
	v_mov_b32_e32 v102, v221
	v_mov_b32_e32 v103, v223
	v_mov_b32_e32 v104, v252
	v_mov_b32_e32 v105, v253
	v_mov_b32_e32 v202, v240
	v_mov_b32_e32 v203, v241
	v_mov_b32_e32 v204, v242
	v_mov_b32_e32 v205, v243

.Lxl_d_2:
	v_lshl_add_u64 v[98:99], v[0:1], 1, s[10:11]
	s_cmp_lg_u32 s98, 0
	s_cbranch_scc1 .Lxr_g3
	global_load_dwordx4 v[114:117], v[98:99], off
.Lxr_g3:
	v_add_u32_e32 v98, 0x4000, v0
	v_mov_b32_e32 v99, v1
	v_lshl_add_u64 v[98:99], v[98:99], 1, s[10:11]
	v_add_u32_e32 v0, 0x8000, v0
	s_cmp_lg_u32 s98, 0
	s_cbranch_scc1 .Lxr_g4
	global_load_dwordx4 v[102:105], v[98:99], off
.Lxr_g4:
	v_lshl_add_u64 v[98:99], v[0:1], 1, s[10:11]
	s_cmp_eq_u32 s98, 0
	s_cbranch_scc1 .Lxl_g_3
	v_mbcnt_lo_u32_b32 v106, -1, 0
	v_mbcnt_hi_u32_b32 v106, -1, v106
	v_readlane_b32 s100, v255, 46
	v_readlane_b32 s101, v255, 47
	v_lshl_add_u32 v106, v106, 4, s99
	s_nop 0
	v_writelane_b32 v98, s100, 63
	v_writelane_b32 v99, s101, 63
	v_readlane_b32 s100, v255, 48
	v_readlane_b32 s101, v255, 49
	s_nop 1
	v_writelane_b32 v100, s100, 63
	v_writelane_b32 v101, s101, 63
	s_bitset0_b64 exec, 63
	ds_read_b128 v[98:101], v106 offset:3072
	s_mov_b64 exec, -1
	s_branch .Lxl_d_3
.Lxl_g_3:
	global_load_dwordx4 v[98:101], v[98:99], off
.Lxl_d_3:
	s_cmp_lt_i32 s16, 42
	s_cselect_b32 s0, s0, s1
	s_bitcmp1_b32 s0, 0
	s_cselect_b64 s[4:5], -1, 0
	s_mul_i32 s68, s12, 0x1800
	s_movk_i32 s0, 0x1fff
	s_and_b64 vcc, exec, s[4:5]
	v_mov_b64_e32 v[106:107], s[68:69]
	v_cmp_lt_i32_e64 s[0:1], s0, v249
	s_cbranch_vccnz .LBB0_896
	s_add_i32 s12, s14, 0xffffe000
	s_lshr_b32 s12, s12, 10
	s_mulk_i32 s12, 0x1800
	s_addk_i32 s12, 0x1800
	v_mov_b32_e32 v0, s12
	v_cndmask_b32_e64 v0, 0, v0, s[0:1]
	v_mov_b64_e32 v[106:107], v[0:1]

.Lxr_d2:
	v_add_u32_e32 v118, 0x4000, v0
	v_mov_b32_e32 v119, v1
	v_add_u32_e32 v0, 0x8000, v0
	v_lshl_add_u64 v[118:119], v[118:119], 1, s[10:11]
	v_lshl_add_u64 v[120:121], v[0:1], 1, s[10:11]
	global_load_dwordx4 v[142:145], v[118:119], off
	s_nop 0
	s_cmp_eq_u32 s98, 0
	s_cbranch_scc1 .Lxr_g5
	v_mov_b32_e32 v118, v202
	v_mov_b32_e32 v119, v203
	v_mov_b32_e32 v120, v204
	v_mov_b32_e32 v121, v205
	s_branch .Lxr_d5
.Lxr_g5:
	global_load_dwordx4 v[118:121], v[120:121], off
.Lxr_d5:
	s_and_b64 vcc, exec, s[0:1]
	v_mov_b64_e32 v[130:131], s[68:69]
	s_cbranch_vccnz .LBB0_908
	s_add_i32 s4, s14, 0xffffe000
	s_lshr_b32 s4, s4, 10
	s_mulk_i32 s4, 0x1800
	s_addk_i32 s4, 0x1800
	v_mov_b32_e32 v0, s4
	s_movk_i32 s4, 0x1fff
	v_cmp_lt_i32_e32 vcc, s4, v249
	s_nop 1
	v_cndmask_b32_e32 v0, 0, v0, vcc
	v_mov_b64_e32 v[130:131], v[0:1]

.LBB0_967:
	v_lshlrev_b64 v[2:3], 1, v[0:1]
	v_cvt_pk_bf16_f32 v120, v48, v49
	v_cvt_pk_bf16_f32 v121, v50, v51
	v_cvt_pk_bf16_f32 v122, v56, v57
	v_cvt_pk_bf16_f32 v123, v58, v59
	v_lshl_add_u64 v[124:125], s[10:11], 0, v[2:3]
	v_mov_b32_e32 v244, v120
	v_mov_b32_e32 v245, v121
	v_mov_b32_e32 v250, v122
	v_mov_b32_e32 v251, v123
	v_lshl_add_u64 v[2:3], s[78:79], 0, v[2:3]
	s_nop 0
	v_pk_fma_f32 v[122:123], v[50:51], v[38:39], v[26:27]
	v_pk_fma_f32 v[120:121], v[48:49], v[36:37], v[24:25]
	v_pk_fma_f32 v[124:125], v[58:59], v[42:43], v[34:35]
	v_pk_fma_f32 v[130:131], v[56:57], v[40:41], v[32:33]
	v_cvt_pk_bf16_f32 v120, v120, v121
	v_cvt_pk_bf16_f32 v121, v122, v123
	v_cvt_pk_bf16_f32 v123, v124, v125
	s_nop 0
	v_cvt_pk_bf16_f32 v122, v130, v131
	global_store_dwordx4 v[2:3], v[120:123], off
	s_branch .LBB0_969

.LBB0_972:
	v_lshlrev_b64 v[2:3], 1, v[0:1]
	v_cvt_pk_bf16_f32 v120, v52, v53
	v_cvt_pk_bf16_f32 v121, v54, v55
	v_cvt_pk_bf16_f32 v122, v56, v57
	v_cvt_pk_bf16_f32 v123, v58, v59
	v_lshl_add_u64 v[116:117], s[10:11], 0, v[2:3]
	v_mov_b32_e32 v221, v120
	v_mov_b32_e32 v223, v121
	v_mov_b32_e32 v252, v122
	v_mov_b32_e32 v253, v123
	v_lshl_add_u64 v[2:3], s[78:79], 0, v[2:3]
	s_nop 0
	v_pk_fma_f32 v[120:121], v[52:53], v[44:45], v[28:29]
	v_pk_fma_f32 v[122:123], v[56:57], v[48:49], v[20:21]
	v_pk_fma_f32 v[116:117], v[54:55], v[46:47], v[30:31]
	v_pk_fma_f32 v[124:125], v[58:59], v[50:51], v[22:23]
	v_cvt_pk_bf16_f32 v120, v120, v121
	v_cvt_pk_bf16_f32 v121, v116, v117
	v_cvt_pk_bf16_f32 v122, v122, v123
	s_nop 0
	v_cvt_pk_bf16_f32 v123, v124, v125
	global_store_dwordx4 v[2:3], v[120:123], off
	s_branch .LBB0_974

.LBB0_977:
	v_lshlrev_b64 v[2:3], 1, v[0:1]
	v_cvt_pk_bf16_f32 v8, v12, v13
	v_cvt_pk_bf16_f32 v9, v14, v15
	v_cvt_pk_bf16_f32 v10, v4, v5
	v_cvt_pk_bf16_f32 v11, v6, v7
	v_lshl_add_u64 v[16:17], s[10:11], 0, v[2:3]
	v_readlane_b32 s100, v8, 63
	v_readlane_b32 s101, v9, 63
	v_mbcnt_lo_u32_b32 v16, -1, 0
	v_mbcnt_hi_u32_b32 v16, -1, v16
	v_writelane_b32 v255, s100, 46
	v_writelane_b32 v255, s101, 47
	v_readlane_b32 s100, v10, 63
	v_readlane_b32 s101, v11, 63
	v_lshl_add_u32 v16, v16, 4, s99
	s_nop 0
	v_writelane_b32 v255, s100, 48
	v_writelane_b32 v255, s101, 49
	s_bitset0_b64 exec, 63
	ds_write_b128 v16, v[8:11] offset:3072
	s_mov_b64 exec, -1
	v_lshl_add_u64 v[2:3], s[78:79], 0, v[2:3]
	s_nop 0
	v_pk_fma_f32 v[10:11], v[14:15], v[46:47], v[30:31]
	v_pk_fma_f32 v[8:9], v[12:13], v[44:45], v[28:29]
	v_pk_fma_f32 v[16:17], v[6:7], v[50:51], v[22:23]
	v_pk_fma_f32 v[18:19], v[4:5], v[48:49], v[20:21]
	v_cvt_pk_bf16_f32 v8, v8, v9
	v_cvt_pk_bf16_f32 v9, v10, v11
	v_cvt_pk_bf16_f32 v11, v16, v17
	s_nop 0
	v_cvt_pk_bf16_f32 v10, v18, v19
	global_store_dwordx4 v[2:3], v[8:11], off
	s_branch .LBB0_979

.LBB0_1016:
	v_lshlrev_b64 v[2:3], 1, v[0:1]
	v_cvt_pk_bf16_f32 v8, v12, v13
	v_cvt_pk_bf16_f32 v9, v14, v15
	v_cvt_pk_bf16_f32 v10, v4, v5
	v_cvt_pk_bf16_f32 v11, v6, v7
	v_lshl_add_u64 v[16:17], s[10:11], 0, v[2:3]
	v_mov_b32_e32 v240, v8
	v_mov_b32_e32 v241, v9
	v_mov_b32_e32 v242, v10
	v_mov_b32_e32 v243, v11
	v_lshl_add_u64 v[2:3], s[78:79], 0, v[2:3]
	s_nop 0
	v_pk_fma_f32 v[10:11], v[14:15], v[38:39], v[30:31]
	v_pk_fma_f32 v[8:9], v[12:13], v[36:37], v[28:29]
	v_pk_fma_f32 v[16:17], v[6:7], v[46:47], v[22:23]
	v_pk_fma_f32 v[18:19], v[4:5], v[44:45], v[20:21]
	v_cvt_pk_bf16_f32 v8, v8, v9
	v_cvt_pk_bf16_f32 v9, v10, v11
	v_cvt_pk_bf16_f32 v11, v16, v17
	s_nop 0
	v_cvt_pk_bf16_f32 v10, v18, v19
	global_store_dwordx4 v[2:3], v[8:11], off
	s_branch .LBB0_1018
